# split-K tail tiles (out-proj, MLP-down): partial-tile stores of the 192 padding rows skipped (only wr=0 waves, A half 0) and the fix-up reads no partials for them (on v74)
# speedup vs baseline: 1.0182x; 1.0113x over previous
.LBB0_576:
	s_lshl_b32 s7, s16, 5
	s_lshl_b32 s6, s6, 2
	s_add_i32 s6, s6, s7
	s_add_i32 s6, s6, s57
	s_addk_i32 s6, 0xfc00
	s_ashr_i32 s7, s6, 31
	s_lshl_b64 s[6:7], s[6:7], 18
	s_waitcnt lgkmcnt(0)
	v_lshl_add_u64 v[150:151], v[144:145], 0, s[6:7]
	s_and_b64 vcc, exec, s[44:45]
	s_cbranch_vccz .Lmy_pr_outproj_done
	global_store_dwordx4 v[150:151], v[132:135], off
	global_store_dwordx4 v[150:151], v[128:131], off offset:16
	global_store_dwordx4 v[150:151], v[116:119], off offset:512
	global_store_dwordx4 v[150:151], v[102:105], off offset:528
	s_nop 1
	v_add_co_u32_e32 v102, vcc, 0x4000, v150
	s_nop 1
	v_addc_co_u32_e32 v103, vcc, 0, v151, vcc
	global_store_dwordx4 v[102:103], v[124:127], off
	global_store_dwordx4 v[102:103], v[120:123], off offset:16
	global_store_dwordx4 v[102:103], v[94:97], off offset:512
	global_store_dwordx4 v[102:103], v[86:89], off offset:528
	s_nop 1
	v_add_co_u32_e32 v86, vcc, 0x8000, v150
	s_nop 1
	v_addc_co_u32_e32 v87, vcc, 0, v151, vcc
	global_store_dwordx4 v[86:87], v[106:109], off
	global_store_dwordx4 v[86:87], v[98:101], off offset:16
	global_store_dwordx4 v[86:87], v[78:81], off offset:512
	global_store_dwordx4 v[86:87], v[74:77], off offset:528
	s_nop 1
	v_add_co_u32_e32 v74, vcc, 0xc000, v150
	s_nop 1
	v_addc_co_u32_e32 v75, vcc, 0, v151, vcc
	global_store_dwordx4 v[74:75], v[90:93], off
	global_store_dwordx4 v[74:75], v[82:85], off offset:16
	global_store_dwordx4 v[74:75], v[70:73], off offset:512
	global_store_dwordx4 v[74:75], v[66:69], off offset:528
	s_branch .Lmy_pr_outproj_done
	s_nop 1
	v_add_co_u32_e32 v66, vcc, 0x20000, v150
	s_nop 1
	v_addc_co_u32_e32 v67, vcc, 0, v151, vcc
	global_store_dwordx4 v[66:67], v[62:65], off
	global_store_dwordx4 v[66:67], v[58:61], off offset:16
	global_store_dwordx4 v[66:67], v[46:49], off offset:512
	global_store_dwordx4 v[66:67], v[38:41], off offset:528
	s_nop 1
	v_add_co_u32_e32 v38, vcc, 0x24000, v150
	s_nop 1
	v_addc_co_u32_e32 v39, vcc, 0, v151, vcc
	global_store_dwordx4 v[38:39], v[54:57], off
	global_store_dwordx4 v[38:39], v[50:53], off offset:16
	global_store_dwordx4 v[38:39], v[30:33], off offset:512
	global_store_dwordx4 v[38:39], v[22:25], off offset:528
	s_nop 1
	v_add_co_u32_e32 v22, vcc, 0x28000, v150
	s_nop 1
	v_addc_co_u32_e32 v23, vcc, 0, v151, vcc
	global_store_dwordx4 v[22:23], v[42:45], off
	global_store_dwordx4 v[22:23], v[34:37], off offset:16
	global_store_dwordx4 v[22:23], v[14:17], off offset:512
	global_store_dwordx4 v[22:23], v[10:13], off offset:528
	s_nop 1
	v_add_co_u32_e32 v10, vcc, 0x2c000, v150
	s_nop 1
	v_addc_co_u32_e32 v11, vcc, 0, v151, vcc
	global_store_dwordx4 v[10:11], v[26:29], off
	global_store_dwordx4 v[10:11], v[18:21], off offset:16
	global_store_dwordx4 v[10:11], v[6:9], off offset:512
	global_store_dwordx4 v[10:11], v[2:5], off offset:528
.Lmy_pr_outproj_done:
	s_andn2_b64 vcc, exec, s[40:41]
	s_mov_b64 s[6:7], -1
	s_cbranch_vccnz .LBB0_544
.LBB0_577:
	s_andn2_b64 vcc, exec, s[42:43]
	s_cbranch_vccnz .LBB0_543
	s_barrier
	s_branch .LBB0_543

.LBB0_638:
	s_ashr_i32 s6, s16, 3
	s_cmpk_gt_i32 s6, 63
	s_cselect_b32 s99, 1, 0
	s_add_i32 s4, s6, 0x2000
	s_ashr_i32 s5, s4, 31
	s_lshl_b64 s[38:39], s[4:5], 12
	v_lshl_add_u64 v[16:17], v[2:3], 0, s[38:39]
	s_waitcnt lgkmcnt(0)
	global_load_dwordx2 v[192:193], v[16:17], off
	s_cmp_eq_u32 s99, 1
	s_cbranch_scc1 .Lmy_fx_outproj_zero
	s_ashr_i32 s7, s6, 31
	s_lshl_b64 s[6:7], s[6:7], 10
	v_lshl_add_u64 v[22:23], v[4:5], 0, s[6:7]
	global_load_dwordx4 v[218:221], v[22:23], off
	v_add_co_u32_e64 v194, s[38:39], s22, v22
	s_nop 1
	v_addc_co_u32_e64 v195, s[38:39], 0, v23, s[38:39]
	global_load_dwordx4 v[222:225], v[194:195], off
	v_add_co_u32_e64 v194, s[38:39], s24, v22
	s_nop 1
	v_addc_co_u32_e64 v195, s[38:39], 0, v23, s[38:39]
	global_load_dwordx4 v[226:229], v[194:195], off
	v_add_co_u32_e64 v194, s[38:39], s25, v22
	s_nop 1
	v_addc_co_u32_e64 v195, s[38:39], 0, v23, s[38:39]
	global_load_dwordx4 v[230:233], v[194:195], off
	s_branch .Lmy_fx_outproj_join
.Lmy_fx_outproj_zero:
	v_mov_b32_e32 v218, 0
	v_mov_b32_e32 v219, 0
	v_mov_b32_e32 v220, 0
	v_mov_b32_e32 v221, 0
	v_mov_b32_e32 v222, 0
	v_mov_b32_e32 v223, 0
	v_mov_b32_e32 v224, 0
	v_mov_b32_e32 v225, 0
	v_mov_b32_e32 v226, 0
	v_mov_b32_e32 v227, 0
	v_mov_b32_e32 v228, 0
	v_mov_b32_e32 v229, 0
	v_mov_b32_e32 v230, 0
	v_mov_b32_e32 v231, 0
	v_mov_b32_e32 v232, 0
	v_mov_b32_e32 v233, 0
.Lmy_fx_outproj_join:
	s_waitcnt vmcnt(0)
	v_lshlrev_b32_e32 v18, 16, v192
	v_and_b32_e32 v19, 0xffff0000, v192
	v_lshlrev_b32_e32 v20, 16, v193
	v_and_b32_e32 v21, 0xffff0000, v193
	v_pk_add_f32 v[18:19], v[218:219], v[18:19]
	v_pk_add_f32 v[20:21], v[220:221], v[20:21]
	v_pk_add_f32 v[18:19], v[222:223], v[18:19]
	v_pk_add_f32 v[20:21], v[224:225], v[20:21]
	v_pk_add_f32 v[18:19], v[226:227], v[18:19]
	v_pk_add_f32 v[20:21], v[228:229], v[20:21]
	v_pk_add_f32 v[14:15], v[232:233], v[20:21]
	v_pk_add_f32 v[12:13], v[230:231], v[18:19]
	v_mul_f32_e32 v18, v15, v15
	v_mul_f32_e32 v11, v13, v13
	v_fmac_f32_e32 v11, v12, v12
	v_fmac_f32_e32 v18, v14, v14
	v_add_f32_e32 v11, v11, v18
	v_bfe_u32 v18, v12, 16, 1
	v_add3_u32 v12, v12, v18, s23
	v_bfe_u32 v18, v13, 16, 1
	v_lshrrev_b32_e32 v12, 16, v12
	v_add3_u32 v13, v13, v18, s23
	v_and_or_b32 v12, v13, s83, v12
	v_bfe_u32 v13, v14, 16, 1
	v_add3_u32 v13, v14, v13, s23
	v_bfe_u32 v14, v15, 16, 1
	v_lshrrev_b32_e32 v13, 16, v13
	v_add3_u32 v14, v15, v14, s23
	v_and_or_b32 v13, v14, s83, v13
	global_store_dwordx2 v[16:17], v[12:13], off
	ds_bpermute_b32 v12, v1, v11
	s_waitcnt lgkmcnt(0)
	v_add_f32_e32 v11, v11, v12
	ds_bpermute_b32 v12, v6, v11
	s_waitcnt lgkmcnt(0)
	v_add_f32_e32 v11, v11, v12
	ds_bpermute_b32 v12, v7, v11
	s_waitcnt lgkmcnt(0)
	v_add_f32_e32 v11, v11, v12
	ds_bpermute_b32 v12, v8, v11
	s_waitcnt lgkmcnt(0)
	v_add_f32_e32 v11, v11, v12
	ds_bpermute_b32 v12, v9, v11
	s_waitcnt lgkmcnt(0)
	v_add_f32_e32 v11, v11, v12
	ds_bpermute_b32 v12, v10, v11
	s_and_saveexec_b64 s[6:7], vcc
	s_cbranch_execz .LBB0_637
	s_lshl_b64 s[4:5], s[4:5], 7
	s_add_u32 s4, s8, s4
	s_waitcnt lgkmcnt(0)
	v_add_f32_e32 v12, v11, v12
	s_addc_u32 s5, s9, s5
	v_mov_b32_e32 v13, v0
	v_mov_b32_e32 v14, v0
	v_mov_b32_e32 v15, v0
	global_store_dwordx4 v0, v[12:15], s[4:5]
	s_branch .LBB0_637

.LBB0_876:
	s_lshl_b32 s7, s16, 6
	s_lshl_b32 s6, s6, 3
	s_add_i32 s6, s6, s7
	s_add_i32 s6, s6, s56
	s_addk_i32 s6, 0xf800
	s_ashr_i32 s7, s6, 31
	s_lshl_b64 s[6:7], s[6:7], 18
	s_waitcnt lgkmcnt(0)
	v_lshl_add_u64 v[150:151], v[144:145], 0, s[6:7]
	s_and_b64 vcc, exec, s[42:43]
	s_cbranch_vccz .Lmy_pr_mlpdown_done
	global_store_dwordx4 v[150:151], v[132:135], off
	global_store_dwordx4 v[150:151], v[128:131], off offset:16
	global_store_dwordx4 v[150:151], v[116:119], off offset:512
	global_store_dwordx4 v[150:151], v[102:105], off offset:528
	s_nop 1
	v_add_co_u32_e32 v102, vcc, 0x4000, v150
	s_nop 1
	v_addc_co_u32_e32 v103, vcc, 0, v151, vcc
	global_store_dwordx4 v[102:103], v[124:127], off
	global_store_dwordx4 v[102:103], v[120:123], off offset:16
	global_store_dwordx4 v[102:103], v[94:97], off offset:512
	global_store_dwordx4 v[102:103], v[86:89], off offset:528
	s_nop 1
	v_add_co_u32_e32 v86, vcc, 0x8000, v150
	s_nop 1
	v_addc_co_u32_e32 v87, vcc, 0, v151, vcc
	global_store_dwordx4 v[86:87], v[106:109], off
	global_store_dwordx4 v[86:87], v[98:101], off offset:16
	global_store_dwordx4 v[86:87], v[78:81], off offset:512
	global_store_dwordx4 v[86:87], v[74:77], off offset:528
	s_nop 1
	v_add_co_u32_e32 v74, vcc, 0xc000, v150
	s_nop 1
	v_addc_co_u32_e32 v75, vcc, 0, v151, vcc
	global_store_dwordx4 v[74:75], v[90:93], off
	global_store_dwordx4 v[74:75], v[82:85], off offset:16
	global_store_dwordx4 v[74:75], v[70:73], off offset:512
	global_store_dwordx4 v[74:75], v[66:69], off offset:528
	s_branch .Lmy_pr_mlpdown_done
	s_nop 1
	v_add_co_u32_e32 v66, vcc, 0x20000, v150
	s_nop 1
	v_addc_co_u32_e32 v67, vcc, 0, v151, vcc
	global_store_dwordx4 v[66:67], v[62:65], off
	global_store_dwordx4 v[66:67], v[58:61], off offset:16
	global_store_dwordx4 v[66:67], v[46:49], off offset:512
	global_store_dwordx4 v[66:67], v[38:41], off offset:528
	s_nop 1
	v_add_co_u32_e32 v38, vcc, 0x24000, v150
	s_nop 1
	v_addc_co_u32_e32 v39, vcc, 0, v151, vcc
	global_store_dwordx4 v[38:39], v[54:57], off
	global_store_dwordx4 v[38:39], v[50:53], off offset:16
	global_store_dwordx4 v[38:39], v[30:33], off offset:512
	global_store_dwordx4 v[38:39], v[22:25], off offset:528
	s_nop 1
	v_add_co_u32_e32 v22, vcc, 0x28000, v150
	s_nop 1
	v_addc_co_u32_e32 v23, vcc, 0, v151, vcc
	global_store_dwordx4 v[22:23], v[42:45], off
	global_store_dwordx4 v[22:23], v[34:37], off offset:16
	global_store_dwordx4 v[22:23], v[14:17], off offset:512
	global_store_dwordx4 v[22:23], v[10:13], off offset:528
	s_nop 1
	v_add_co_u32_e32 v10, vcc, 0x2c000, v150
	s_nop 1
	v_addc_co_u32_e32 v11, vcc, 0, v151, vcc
	global_store_dwordx4 v[10:11], v[26:29], off
	global_store_dwordx4 v[10:11], v[18:21], off offset:16
	global_store_dwordx4 v[10:11], v[6:9], off offset:512
	global_store_dwordx4 v[10:11], v[2:5], off offset:528
.Lmy_pr_mlpdown_done:
	s_andn2_b64 vcc, exec, s[40:41]
	s_mov_b64 s[6:7], -1
	s_cbranch_vccnz .LBB0_844
.LBB0_877:
	s_andn2_b64 vcc, exec, s[34:35]
	s_cbranch_vccnz .LBB0_843
	s_barrier
	s_branch .LBB0_843

.LBB0_938:
	s_ashr_i32 s6, s16, 3
	s_cmpk_gt_i32 s6, 63
	s_cselect_b32 s99, 1, 0
	s_add_i32 s4, s6, 0x2000
	s_ashr_i32 s5, s4, 31
	s_lshl_b64 s[34:35], s[4:5], 12
	s_waitcnt lgkmcnt(0)
	v_lshl_add_u64 v[6:7], v[2:3], 0, s[34:35]
	global_load_dwordx2 v[192:193], v[6:7], off
	s_cmp_eq_u32 s99, 1
	s_cbranch_scc1 .Lmy_fx_mlpdown_zero
	s_ashr_i32 s7, s6, 31
	s_lshl_b64 s[6:7], s[6:7], 10
	v_lshl_add_u64 v[22:23], v[4:5], 0, s[6:7]
	global_load_dwordx4 v[218:221], v[22:23], off
	v_add_co_u32_e64 v194, s[38:39], s22, v22
	s_nop 1
	v_addc_co_u32_e64 v195, s[38:39], 0, v23, s[38:39]
	global_load_dwordx4 v[222:225], v[194:195], off
	v_add_co_u32_e64 v194, s[38:39], s24, v22
	s_nop 1
	v_addc_co_u32_e64 v195, s[38:39], 0, v23, s[38:39]
	global_load_dwordx4 v[226:229], v[194:195], off
	v_add_co_u32_e64 v194, s[38:39], s25, v22
	s_nop 1
	v_addc_co_u32_e64 v195, s[38:39], 0, v23, s[38:39]
	global_load_dwordx4 v[230:233], v[194:195], off
	v_add_co_u32_e64 v194, s[38:39], s29, v22
	s_nop 1
	v_addc_co_u32_e64 v195, s[38:39], 0, v23, s[38:39]
	global_load_dwordx4 v[234:237], v[194:195], off
	v_add_co_u32_e64 v194, s[38:39], s14, v22
	s_nop 1
	v_addc_co_u32_e64 v195, s[38:39], 0, v23, s[38:39]
	global_load_dwordx4 v[238:241], v[194:195], off
	v_add_co_u32_e64 v194, s[38:39], s15, v22
	s_nop 1
	v_addc_co_u32_e64 v195, s[38:39], 0, v23, s[38:39]
	global_load_dwordx4 v[242:245], v[194:195], off
	v_add_co_u32_e64 v194, s[38:39], s28, v22
	s_nop 1
	v_addc_co_u32_e64 v195, s[38:39], 0, v23, s[38:39]
	global_load_dwordx4 v[188:191], v[194:195], off
	s_branch .Lmy_fx_mlpdown_join
.Lmy_fx_mlpdown_zero:
	v_mov_b32_e32 v218, 0
	v_mov_b32_e32 v219, 0
	v_mov_b32_e32 v220, 0
	v_mov_b32_e32 v221, 0
	v_mov_b32_e32 v222, 0
	v_mov_b32_e32 v223, 0
	v_mov_b32_e32 v224, 0
	v_mov_b32_e32 v225, 0
	v_mov_b32_e32 v226, 0
	v_mov_b32_e32 v227, 0
	v_mov_b32_e32 v228, 0
	v_mov_b32_e32 v229, 0
	v_mov_b32_e32 v230, 0
	v_mov_b32_e32 v231, 0
	v_mov_b32_e32 v232, 0
	v_mov_b32_e32 v233, 0
	v_mov_b32_e32 v234, 0
	v_mov_b32_e32 v235, 0
	v_mov_b32_e32 v236, 0
	v_mov_b32_e32 v237, 0
	v_mov_b32_e32 v238, 0
	v_mov_b32_e32 v239, 0
	v_mov_b32_e32 v240, 0
	v_mov_b32_e32 v241, 0
	v_mov_b32_e32 v242, 0
	v_mov_b32_e32 v243, 0
	v_mov_b32_e32 v244, 0
	v_mov_b32_e32 v245, 0
	v_mov_b32_e32 v188, 0
	v_mov_b32_e32 v189, 0
	v_mov_b32_e32 v190, 0
	v_mov_b32_e32 v191, 0
.Lmy_fx_mlpdown_join:
	s_waitcnt vmcnt(0)
	v_lshlrev_b32_e32 v18, 16, v192
	v_and_b32_e32 v19, 0xffff0000, v192
	v_lshlrev_b32_e32 v20, 16, v193
	v_and_b32_e32 v21, 0xffff0000, v193
	v_pk_add_f32 v[18:19], v[218:219], v[18:19]
	v_pk_add_f32 v[20:21], v[220:221], v[20:21]
	v_pk_add_f32 v[18:19], v[222:223], v[18:19]
	v_pk_add_f32 v[20:21], v[224:225], v[20:21]
	v_pk_add_f32 v[18:19], v[226:227], v[18:19]
	v_pk_add_f32 v[20:21], v[228:229], v[20:21]
	v_pk_add_f32 v[18:19], v[230:231], v[18:19]
	v_pk_add_f32 v[20:21], v[232:233], v[20:21]
	v_pk_add_f32 v[18:19], v[234:235], v[18:19]
	v_pk_add_f32 v[20:21], v[236:237], v[20:21]
	v_pk_add_f32 v[18:19], v[238:239], v[18:19]
	v_pk_add_f32 v[20:21], v[240:241], v[20:21]
	v_pk_add_f32 v[18:19], v[242:243], v[18:19]
	v_pk_add_f32 v[20:21], v[244:245], v[20:21]
	v_pk_add_f32 v[16:17], v[190:191], v[20:21]
	v_pk_add_f32 v[14:15], v[188:189], v[18:19]
	v_mul_f32_e32 v18, v17, v17
	v_mul_f32_e32 v13, v15, v15
	v_fmac_f32_e32 v13, v14, v14
	v_fmac_f32_e32 v18, v16, v16
	v_add_f32_e32 v13, v13, v18
	v_bfe_u32 v18, v14, 16, 1
	v_add3_u32 v14, v14, v18, s23
	v_bfe_u32 v18, v15, 16, 1
	v_lshrrev_b32_e32 v14, 16, v14
	v_add3_u32 v15, v15, v18, s23
	v_and_or_b32 v14, v15, s83, v14
	v_bfe_u32 v15, v16, 16, 1
	v_add3_u32 v15, v16, v15, s23
	v_bfe_u32 v16, v17, 16, 1
	v_lshrrev_b32_e32 v15, 16, v15
	v_add3_u32 v16, v17, v16, s23
	v_and_or_b32 v15, v16, s83, v15
	global_store_dwordx2 v[6:7], v[14:15], off
	ds_bpermute_b32 v6, v1, v13
	s_waitcnt lgkmcnt(0)
	v_add_f32_e32 v6, v13, v6
	ds_bpermute_b32 v7, v8, v6
	s_waitcnt lgkmcnt(0)
	v_add_f32_e32 v6, v6, v7
	ds_bpermute_b32 v7, v9, v6
	s_waitcnt lgkmcnt(0)
	v_add_f32_e32 v6, v6, v7
	ds_bpermute_b32 v7, v10, v6
	s_waitcnt lgkmcnt(0)
	v_add_f32_e32 v6, v6, v7
	ds_bpermute_b32 v7, v11, v6
	s_waitcnt lgkmcnt(0)
	v_add_f32_e32 v6, v6, v7
	ds_bpermute_b32 v7, v12, v6
	s_and_saveexec_b64 s[6:7], vcc
	s_cbranch_execz .LBB0_937
	s_lshl_b64 s[4:5], s[4:5], 7
	s_add_u32 s4, s8, s4
	s_waitcnt lgkmcnt(0)
	v_add_f32_e32 v14, v6, v7
	s_addc_u32 s5, s9, s5
	v_mov_b32_e32 v15, v0
	v_mov_b32_e32 v16, v0
	v_mov_b32_e32 v17, v0
	global_store_dwordx4 v0, v[14:17], s[4:5]
	s_branch .LBB0_937
